# attention: K tile staged by LDS-DMA (global_load_lds) instead of VGPR+ds_write; V staging thread-to-piece remap removes the 2-way ds_write_b128 bank conflict
# speedup vs baseline: 1.0030x; 1.0030x over previous
; __device__ __forceinline__ int tidx() { int t = threadIdx.x; asm volatile("" : "+v"(t)); return t; }
; __device__ __forceinline__ void attn_dv256_body(const bf16* __restrict__ Qb, const bf16* __restrict__ Kh, const bf16* __restrict__ Vh,
;                                                 float* __restrict__ Ob, int seq, float kmax, char* lds) {
;     ...
;   const int tid = tidx(), wid = tid >> 6, lane = tid & 63, r32 = lane & 31, hi = lane >> 5;
;   const int rg = wid & 3, kh = wid >> 2;
;   char* V_lds = lds; char* K_lds = lds + 65536; char* XCH = lds + 98304; float* LI = (float*)(lds + 131072);
;   f32x16 o[4] = {}; bf16x8 qr[8];
;   const bf16* Qw = Qb + (long)(rg * 32 + r32) * LDQ + hi * 8;
; #pragma unroll
;   for (int d0 = 0; d0 < 8; ++d0) qr[d0] = St::ld8(Qw + d0 * 16);
;   float qq = 0.f;
; #pragma unroll
;   for (int d0 = 0; d0 < 8; ++d0)
; #pragma unroll
;     for (int e = 0; e < 8; ++e) { const float v = __uint_as_float(((unsigned)(unsigned short)qr[d0][e]) << 16); qq += v * v; }
;   qq += __shfl_xor(qq, 32);
;   constexpr float C = SCALE * 1.4426950408889634f;
;   const float mC = -sqrtf(qq) * kmax * C * 1.002f;
; __device__ __forceinline__ void attn_item(const u16* P, float* AO, const unsigned* kmaxu, int item, char* lds) {
;     int hm, qrow0, krow0, seq;
;     if (item < 512) { hm = item >> 6; qrow0 = (item & 63) * 128; krow0 = 0; seq = TT; }
;     else { hm = (item - 512) >> 1; qrow0 = TL + ((item - 512) & 1) * 128; krow0 = TL; seq = TC; }
;     const int h = hm >> 1;
;     const att::bf16* Pb = (const att::bf16*)P;
;     const att::bf16* Q = Pb + (size_t)qrow0 * PST + C_CQ + hm * 128;
;     const att::bf16* K = Pb + (size_t)krow0 * PST + C_CK + hm * 128;
;     const att::bf16* V = Pb + (size_t)krow0 * PST + C_CV + h * 256;
;     float* O = AO + (size_t)qrow0 * DM + hm * 256;
;     const float kmax = sqrtf(__uint_as_float(kmaxu[hm]));
;     att::attn_dv256_body(Q, K, V, O, seq, kmax, lds);
.LBB0_909:
	s_mul_i32 s7, s84, 0x4080
	s_mul_hi_u32 s1, s84, 0x4080
	s_add_u32 s7, s78, s7
	s_addc_u32 s1, s79, s1
	s_lshl_b32 s22, s34, 7
	s_ashr_i32 s23, s22, 31
	s_lshl_b64 s[38:39], s[22:23], 1
	s_add_u32 s42, s7, s38
	s_addc_u32 s43, s1, s39
	s_lshl_b32 s0, s0, 1
	s_add_u32 s7, s78, s0
	s_addc_u32 s13, s79, 0
	s_add_u32 s0, s7, s38
	s_addc_u32 s1, s13, s39
	s_add_u32 s38, s0, 0x2800
	s_addc_u32 s39, s1, 0
	s_and_b32 s0, s22, 0xffffff00
	s_ashr_i32 s1, s0, 31
	s_lshl_b64 s[0:1], s[0:1], 1
	s_add_u32 s0, s7, s0
	s_addc_u32 s1, s13, s1
	s_add_u32 s40, s0, 0x3000
	s_addc_u32 s41, s1, 0
	s_ashr_i32 s35, s34, 31
	s_lshl_b64 s[0:1], s[34:35], 2
	s_add_u32 s0, s20, s0
	s_addc_u32 s1, s21, s1
	v_mov_b32_e32 v3, v170
	global_load_dword v6, v165, s[0:1]
	s_mov_b64 s[0:1], 0x2000
	v_ashrrev_i32_e32 v2, 6, v3
	v_lshlrev_b32_e32 v0, 5, v2
	v_and_b32_e32 v186, 31, v3
	v_and_b32_e32 v185, 0x60, v0
	v_or_b32_e32 v0, v185, v186
	v_mul_u32_u24_e32 v0, 0x2040, v0
	v_bfe_u32 v184, v3, 5, 1
	v_lshlrev_b32_e32 v164, 1, v0
	v_lshl_add_u64 v[0:1], s[42:43], 0, v[164:165]
	v_lshlrev_b32_e32 v164, 4, v184
	v_lshl_add_u64 v[0:1], v[0:1], 0, v[164:165]
	v_add_co_u32_e32 v4, vcc, s95, v0
	s_mov_b32 s22, 0xf800000
	s_nop 0
	v_addc_co_u32_e32 v5, vcc, 0, v1, vcc
	global_load_dwordx4 v[80:83], v[4:5], off
	v_lshl_add_u64 v[0:1], v[0:1], 0, s[0:1]
	global_load_dwordx4 v[84:87], v[0:1], off offset:32
	global_load_dwordx4 v[88:91], v[0:1], off offset:64
	global_load_dwordx4 v[92:95], v[0:1], off offset:96
	global_load_dwordx4 v[96:99], v[0:1], off offset:128
	global_load_dwordx4 v[100:103], v[0:1], off offset:160
	global_load_dwordx4 v[104:107], v[0:1], off offset:192
	global_load_dwordx4 v[108:111], v[0:1], off offset:224
	v_ashrrev_i32_e32 v189, 4, v3
	v_add_u32_e32 v190, 32, v189
	s_movk_i32 s13, 0x2040
	s_cmp_lg_u32 0, -1
	v_ashrrev_i32_e32 v187, 8, v3
	v_and_b32_e32 v191, 63, v3
	v_lshlrev_b32_e32 v205, 4, v191
	v_mov_b32_e32 v132, 0
	v_mov_b32_e32 v144, 0
	v_mov_b32_e32 v192, 0
	s_mov_b32 s7, 0
	v_lshlrev_b32_e32 v209, 11, v2
	v_mov_b32_e32 v2, v192
	v_mov_b32_e32 v55, v192
	v_mov_b32_e32 v56, v192
	v_mov_b32_e32 v57, v192
	v_mov_b32_e32 v58, v192
	v_mov_b32_e32 v59, v192
	v_mov_b32_e32 v60, v192
	v_mov_b32_e32 v61, v192
	v_mov_b32_e32 v62, v192
	v_mov_b32_e32 v63, v192
	v_mov_b32_e32 v145, v144
	v_mov_b32_e32 v146, v144
	v_mov_b32_e32 v147, v144
	v_mov_b32_e32 v148, v144
	v_mov_b32_e32 v149, v144
	v_mov_b32_e32 v150, v144
	v_mov_b32_e32 v151, v144
	v_mov_b32_e32 v133, v132
	v_mov_b32_e32 v134, v132
	v_mov_b32_e32 v135, v132
	v_mov_b32_e32 v128, v132
	v_mov_b32_e32 v129, v132
	v_mov_b32_e32 v130, v132
	v_mov_b32_e32 v131, v132
	s_waitcnt vmcnt(8)
	v_mul_f32_e32 v4, 0x4f800000, v6
	v_cmp_gt_f32_e32 vcc, s22, v6
	s_waitcnt vmcnt(6)
	v_lshlrev_b32_e32 v14, 16, v84
	v_cndmask_b32_e32 v4, v6, v4, vcc
	v_sqrt_f32_e32 v7, v4
	v_lshlrev_b32_e32 v8, 16, v81
	v_and_b32_e32 v9, 0xffff0000, v81
	v_lshlrev_b32_e32 v10, 16, v82
	v_add_u32_e32 v0, -1, v7
	v_fma_f32 v1, -v0, v7, v4
	v_add_u32_e32 v5, 1, v7
	v_cmp_ge_f32_e64 s[0:1], 0, v1
	v_and_b32_e32 v1, 0xffff0000, v80
	v_fma_f32 v6, -v5, v7, v4
	v_cndmask_b32_e64 v7, v7, v0, s[0:1]
	v_lshlrev_b32_e32 v0, 16, v80
	v_mul_f32_e32 v54, v1, v1
	v_fmac_f32_e32 v54, v0, v0
	v_fmac_f32_e32 v54, v8, v8
	v_fmac_f32_e32 v54, v9, v9
	v_and_b32_e32 v11, 0xffff0000, v82
	v_fmac_f32_e32 v54, v10, v10
	v_lshlrev_b32_e32 v12, 16, v83
	v_fmac_f32_e32 v54, v11, v11
	v_and_b32_e32 v13, 0xffff0000, v83
	v_fmac_f32_e32 v54, v12, v12
	v_fmac_f32_e32 v54, v13, v13
	v_and_b32_e32 v15, 0xffff0000, v84
	v_fmac_f32_e32 v54, v14, v14
	v_lshlrev_b32_e32 v16, 16, v85
	v_fmac_f32_e32 v54, v15, v15
	v_and_b32_e32 v17, 0xffff0000, v85
	v_fmac_f32_e32 v54, v16, v16
	v_lshlrev_b32_e32 v18, 16, v86
	v_fmac_f32_e32 v54, v17, v17
	v_and_b32_e32 v19, 0xffff0000, v86
	v_fmac_f32_e32 v54, v18, v18
	v_lshlrev_b32_e32 v20, 16, v87
	v_fmac_f32_e32 v54, v19, v19
	v_and_b32_e32 v21, 0xffff0000, v87
	v_fmac_f32_e32 v54, v20, v20
	s_waitcnt vmcnt(5)
	v_lshlrev_b32_e32 v22, 16, v88
	v_fmac_f32_e32 v54, v21, v21
	v_and_b32_e32 v23, 0xffff0000, v88
	v_fmac_f32_e32 v54, v22, v22
	v_lshlrev_b32_e32 v24, 16, v89
	v_fmac_f32_e32 v54, v23, v23
	v_and_b32_e32 v25, 0xffff0000, v89
	v_fmac_f32_e32 v54, v24, v24
	v_lshlrev_b32_e32 v26, 16, v90
	v_fmac_f32_e32 v54, v25, v25
	v_and_b32_e32 v27, 0xffff0000, v90
	v_fmac_f32_e32 v54, v26, v26
	v_lshlrev_b32_e32 v28, 16, v91
	v_fmac_f32_e32 v54, v27, v27
	v_and_b32_e32 v29, 0xffff0000, v91
	v_fmac_f32_e32 v54, v28, v28
	s_waitcnt vmcnt(4)
	v_lshlrev_b32_e32 v30, 16, v92
	v_fmac_f32_e32 v54, v29, v29
	v_and_b32_e32 v31, 0xffff0000, v92
	v_fmac_f32_e32 v54, v30, v30
	v_lshlrev_b32_e32 v32, 16, v93
	v_fmac_f32_e32 v54, v31, v31
	v_and_b32_e32 v33, 0xffff0000, v93
	v_fmac_f32_e32 v54, v32, v32
	v_lshlrev_b32_e32 v34, 16, v94
	v_fmac_f32_e32 v54, v33, v33
	v_and_b32_e32 v35, 0xffff0000, v94
	v_fmac_f32_e32 v54, v34, v34
	v_lshlrev_b32_e32 v36, 16, v95
	v_fmac_f32_e32 v54, v35, v35
	v_and_b32_e32 v37, 0xffff0000, v95
	v_fmac_f32_e32 v54, v36, v36
	s_waitcnt vmcnt(3)
	v_lshlrev_b32_e32 v38, 16, v96
	v_fmac_f32_e32 v54, v37, v37
	v_and_b32_e32 v39, 0xffff0000, v96
	v_fmac_f32_e32 v54, v38, v38
	v_lshlrev_b32_e32 v40, 16, v97
	v_fmac_f32_e32 v54, v39, v39
	v_and_b32_e32 v41, 0xffff0000, v97
	v_fmac_f32_e32 v54, v40, v40
	v_lshlrev_b32_e32 v42, 16, v98
	v_fmac_f32_e32 v54, v41, v41
	v_and_b32_e32 v43, 0xffff0000, v98
	v_fmac_f32_e32 v54, v42, v42
	v_lshlrev_b32_e32 v44, 16, v99
	v_fmac_f32_e32 v54, v43, v43
	v_and_b32_e32 v45, 0xffff0000, v99
	v_fmac_f32_e32 v54, v44, v44
	s_waitcnt vmcnt(2)
; __device__ __forceinline__ int v_st(int k, int c) { const int kk = (k & ~0xC) | ((k & 4) << 1) | ((k & 8) >> 1); return ((kk >> 3) * 4 + (c >> 5)) * 512 + ((kk & 7) * 32 + (c & 31)) * 2; }
; __device__ __forceinline__ int v_rd_base(int lane) { return ((lane & 3) << 3) | (((lane >> 2) & 3) << 6) | (((lane >> 4) & 1) << 5) | (((lane >> 5) & 1) << 8); }
; #define KLOAD(k0) do { kr0 = St::ld8(&Kh[(long)((k0) + sr) * LDK + sc]); kr1 = St::ld8(&Kh[(long)((k0) + 32 + sr) * LDK + sc]); } while (0)
; #define VLOAD(k0) do { vr0 = St::ld8(&Vh[(long)((k0) + sr) * LDK + sc]); vr1 = St::ld8(&Vh[(long)((k0) + 32 + sr) * LDK + sc]); \
;     vr2 = St::ld8(&Vh[(long)((k0) + sr) * LDK + 128 + sc]); vr3 = St::ld8(&Vh[(long)((k0) + 32 + sr) * LDK + 128 + sc]); } while (0)
; #define KWRITE(b) do { *(bf16x8*)(K_lds + (b) * 16384 + KSWZ(sr, sc * 2)) = kr0; *(bf16x8*)(K_lds + (b) * 16384 + KSWZ(32 + sr, sc * 2)) = kr1; } while (0)
; #define VWRITE(b) do { *(bf16x8*)(V_lds + ((b) * 2) * 16384 + vst0) = vr0; *(bf16x8*)(V_lds + ((b) * 2) * 16384 + vst1) = vr1; \
;     *(bf16x8*)(V_lds + ((b) * 2 + 1) * 16384 + vst1) = vr2; *(bf16x8*)(V_lds + ((b) * 2 + 1) * 16384 + vst0) = vr3; } while (0)
; __device__ __forceinline__ void attn_dv256_body(const bf16* __restrict__ Qb, const bf16* __restrict__ Kh, const bf16* __restrict__ Vh,
;                                                 float* __restrict__ Ob, int seq, float kmax, char* lds) {
;     ...
;   const int sr = tid >> 4, sc = (tid & 15) * 8, vst0 = v_st(sr, sc), vst1 = v_st(32 + sr, sc);
;   const int vb0 = (int)(uintptr_t)V_lds + kh * 16384 + v_rd_base(lane);
;   bf16x8 kr0, kr1, vr0, vr1, vr2, vr3;
;     ...
;   const int NT = seq / KVBLK;
;   f32x16 pc, pn; pn = f32x16{};
;   bf16x8 q0 = {}, q1 = {}, q2 = {}, q3 = {};
;   char* XC0 = XCH;
;   KLOAD(0); VLOAD(0); asm volatile("s_waitcnt vmcnt(0)" ::: "memory"); KWRITE(0); VWRITE(0);
;   KLOAD(KVBLK); VLOAD(KVBLK); asm volatile("s_waitcnt vmcnt(0)" ::: "memory"); KWRITE(1); VWRITE(1);
;   __syncthreads();
	v_lshlrev_b32_e32 v46, 16, v100
	v_fmac_f32_e32 v54, v45, v45
	v_and_b32_e32 v47, 0xffff0000, v100
	v_fmac_f32_e32 v54, v46, v46
	v_lshlrev_b32_e32 v48, 16, v101
	v_fmac_f32_e32 v54, v47, v47
	v_and_b32_e32 v49, 0xffff0000, v101
	v_fmac_f32_e32 v54, v48, v48
	v_lshlrev_b32_e32 v50, 16, v102
	v_fmac_f32_e32 v54, v49, v49
	v_lshlrev_b32_e32 v49, 3, v3
	v_and_b32_e32 v51, 0xffff0000, v102
	v_fmac_f32_e32 v54, v50, v50
	v_and_b32_e32 v32, 0x78, v49
	v_mov_b32_e32 v33, v165
	v_lshlrev_b32_e32 v52, 16, v103
	v_fmac_f32_e32 v54, v51, v51
	v_mad_i64_i32 v[8:9], s[0:1], v189, s13, v[32:33]
	v_mad_i64_i32 v[10:11], s[0:1], v190, s13, v[32:33]
	v_and_b32_e32 v53, 0xffff0000, v103
	v_fmac_f32_e32 v54, v52, v52
	v_lshlrev_b64 v[16:17], 1, v[8:9]
	v_lshlrev_b64 v[18:19], 1, v[10:11]
	v_fmac_f32_e32 v54, v53, v53
	s_waitcnt vmcnt(1)
	v_lshlrev_b32_e32 v0, 16, v104
	v_lshl_add_u64 v[8:9], s[38:39], 0, v[16:17]
	v_lshl_add_u64 v[12:13], s[38:39], 0, v[18:19]
	v_fmac_f32_e32 v54, v0, v0
	v_and_b32_e32 v0, 0xffff0000, v104
	v_mad_i64_i32 v[24:25], s[0:1], v189, s13, 0
	v_mad_i64_i32 v[26:27], s[0:1], v190, s13, 0
	global_load_dwordx4 v[8:11], v[8:9], off
	s_nop 0
	global_load_dwordx4 v[12:15], v[12:13], off
	v_add_u32_e32 v34, 64, v189
	v_add_u32_e32 v36, 0x60, v189
	v_fmac_f32_e32 v54, v0, v0
	v_lshlrev_b32_e32 v0, 1, v32
	v_lshl_add_u64 v[24:25], v[24:25], 1, s[40:41]
	v_mov_b32_e32 v1, v165
	v_lshl_add_u64 v[26:27], v[26:27], 1, s[40:41]
	v_mad_i64_i32 v[40:41], s[0:1], v34, s13, 0
	v_mad_i64_i32 v[34:35], s[0:1], v34, s13, v[32:33]
	v_mad_i64_i32 v[32:33], s[0:1], v36, s13, v[32:33]
	v_lshl_add_u64 v[16:17], s[40:41], 0, v[16:17]
	v_lshl_add_u64 v[20:21], s[40:41], 0, v[18:19]
	v_lshl_add_u64 v[24:25], v[24:25], 0, v[0:1]
	v_lshl_add_u64 v[28:29], v[26:27], 0, v[0:1]
	v_lshlrev_b64 v[42:43], 1, v[34:35]
	v_lshlrev_b64 v[46:47], 1, v[32:33]
	global_load_dwordx4 v[16:19], v[16:17], off
	s_nop 0
	global_load_dwordx4 v[20:23], v[20:21], off
	s_nop 0
	global_load_dwordx4 v[24:27], v[24:25], off offset:256
	s_nop 0
	global_load_dwordx4 v[28:31], v[28:29], off offset:256
	s_waitcnt vmcnt(0)
	v_lshl_add_u64 v[34:35], s[38:39], 0, v[42:43]
	v_mad_i64_i32 v[44:45], s[0:1], v36, s13, 0
	v_lshl_add_u64 v[36:37], s[38:39], 0, v[46:47]
	v_lshl_add_u64 v[42:43], s[40:41], 0, v[42:43]
	v_lshl_add_u64 v[40:41], v[40:41], 1, s[40:41]
	global_load_dwordx4 v[32:35], v[34:35], off
	s_nop 0
	global_load_dwordx4 v[36:39], v[36:37], off
	v_lshl_add_u64 v[46:47], s[40:41], 0, v[46:47]
	global_load_dwordx4 v[116:119], v[42:43], off
	global_load_dwordx4 v[112:115], v[46:47], off
	v_lshl_add_u64 v[40:41], v[40:41], 0, v[0:1]
	v_lshl_add_u64 v[42:43], v[44:45], 1, s[40:41]
	v_lshl_add_u64 v[42:43], v[42:43], 0, v[0:1]
	global_load_dwordx4 v[120:123], v[40:41], off offset:256
	global_load_dwordx4 v[124:127], v[42:43], off offset:256
	v_lshlrev_b32_e32 v48, 16, v105
	v_fmac_f32_e32 v54, v48, v48
	v_and_b32_e32 v40, 0xffff0000, v105
	v_fmac_f32_e32 v54, v40, v40
	v_lshlrev_b32_e32 v40, 16, v106
	v_fmac_f32_e32 v54, v40, v40
	v_and_b32_e32 v40, 0xffff0000, v106
	v_fmac_f32_e32 v54, v40, v40
	v_lshlrev_b32_e32 v40, 16, v107
	v_fmac_f32_e32 v54, v40, v40
	v_and_b32_e32 v40, 0xffff0000, v107
	v_and_b32_e32 v41, 0xfffff0, v189
	v_lshlrev_b32_e32 v42, 1, v189
	v_fmac_f32_e32 v54, v40, v40
	s_waitcnt vmcnt(12)
	v_lshlrev_b32_e32 v40, 16, v108
	v_and_or_b32 v41, v42, 8, v41
	v_fmac_f32_e32 v54, v40, v40
	v_and_b32_e32 v40, 0xffff0000, v108
	v_lshrrev_b32_e32 v42, 1, v189
	v_lshrrev_b32_e32 v41, 1, v41
	v_bfe_u32 v43, v49, 5, 2
	v_and_b32_e32 v44, 3, v189
	v_fmac_f32_e32 v54, v40, v40
	v_lshlrev_b32_e32 v40, 16, v109
	v_or_b32_e32 v41, v41, v43
	v_and_or_b32 v42, v42, 4, v44
	v_fmac_f32_e32 v54, v40, v40
	v_and_b32_e32 v40, 0xffff0000, v109
	v_lshlrev_b32_e32 v41, 9, v41
	v_lshlrev_b32_e32 v42, 6, v42
	v_and_b32_e32 v44, 48, v0
	v_fmac_f32_e32 v54, v40, v40
	v_lshlrev_b32_e32 v40, 16, v110
	v_or3_b32 v193, v41, v42, v44
	v_and_b32_e32 v41, 0xfffff0, v190
	v_lshlrev_b32_e32 v45, 1, v190
	v_fmac_f32_e32 v54, v40, v40
	v_and_b32_e32 v40, 0xffff0000, v110
	v_and_or_b32 v41, v45, 8, v41
	v_fmac_f32_e32 v54, v40, v40
	v_lshlrev_b32_e32 v40, 16, v111
	v_lshrrev_b32_e32 v41, 1, v41
	v_fmac_f32_e32 v54, v40, v40
	v_and_b32_e32 v40, 0xffff0000, v111
	v_or_b32_e32 v41, v41, v43
	v_fmac_f32_e32 v54, v40, v40
	v_xor_b32_e32 v40, 32, v171
	v_lshlrev_b32_e32 v41, 9, v41
	v_cmp_lt_i32_e64 s[0:1], v40, v172
	v_or3_b32 v194, v41, v42, v44
	v_lshlrev_b32_e32 v41, 8, v189
	v_and_b32_e32 v42, 0x70, v3
	v_cndmask_b32_e64 v40, v171, v40, s[0:1]
	s_cselect_b32 s13, 0, 0
	v_bitop3_b32 v195, v0, v41, v42 bitop3:0xde
	s_add_i32 s0, 0, 0x10000
	v_add_u32_e32 v41, s0, v195
	s_waitcnt vmcnt(11)
	ds_write_b128 v41, v[8:11]
	v_lshlrev_b32_e32 v8, 8, v190
	v_bitop3_b32 v196, v0, v8, v42 bitop3:0xde
	v_add_u32_e32 v8, s0, v196
	s_waitcnt vmcnt(10)
	ds_write_b128 v8, v[12:15]
	v_add_u32_e32 v8, 0, v193
	v_add_u32_e32 v9, 0, v194
	s_add_i32 s1, 0, 0x14000
	s_waitcnt vmcnt(9)
	ds_write_b128 v8, v[16:19]
	s_waitcnt vmcnt(8)
	ds_write_b128 v9, v[20:23]
	s_waitcnt vmcnt(7)
	ds_write_b128 v9, v[24:27] offset:16384
	s_waitcnt vmcnt(6)
	ds_write_b128 v8, v[28:31] offset:16384
	v_add_u32_e32 v10, s1, v195
	s_waitcnt vmcnt(0)
	v_lshlrev_b32_e32 v12, 4, v3
	v_and_b32_e32 v16, 0x70, v12
	v_bitop3_b32 v199, v164, v16, 32 bitop3:0x36
	s_waitcnt vmcnt(5)
	ds_write_b128 v10, v[32:35]
	v_add_u32_e32 v10, s1, v196
	s_waitcnt vmcnt(4)
	ds_write_b128 v10, v[36:39]
	s_waitcnt vmcnt(3)
	ds_write_b128 v8, v[116:119] offset:32768
	s_waitcnt vmcnt(2)
	ds_write_b128 v9, v[112:115] offset:32768
	s_waitcnt vmcnt(1)
	ds_write_b128 v9, v[120:123] offset:49152
	s_waitcnt vmcnt(0)
	ds_write_b128 v8, v[124:127] offset:49152
	v_lshlrev_b32_e32 v8, 13, v187
	v_lshlrev_b32_e32 v9, 8, v186
	v_add3_u32 v197, s0, v8, v9
	s_movk_i32 s0, 0x70
	v_bitop3_b32 v198, v164, v12, s0 bitop3:0x78
	v_add_u32_e32 v8, v197, v198
	s_waitcnt lgkmcnt(0)
	s_barrier
; #define KLOAD(k0) do { kr0 = St::ld8(&Kh[(long)((k0) + sr) * LDK + sc]); kr1 = St::ld8(&Kh[(long)((k0) + 32 + sr) * LDK + sc]); } while (0)
; #define VLOAD(k0) do { vr0 = St::ld8(&Vh[(long)((k0) + sr) * LDK + sc]); vr1 = St::ld8(&Vh[(long)((k0) + 32 + sr) * LDK + sc]); \
;     vr2 = St::ld8(&Vh[(long)((k0) + sr) * LDK + 128 + sc]); vr3 = St::ld8(&Vh[(long)((k0) + 32 + sr) * LDK + 128 + sc]); } while (0)
; #define KWRITE(b) do { *(bf16x8*)(K_lds + (b) * 16384 + KSWZ(sr, sc * 2)) = kr0; *(bf16x8*)(K_lds + (b) * 16384 + KSWZ(32 + sr, sc * 2)) = kr1; } while (0)
; #define VWRITE(b) do { *(bf16x8*)(V_lds + ((b) * 2) * 16384 + vst0) = vr0; *(bf16x8*)(V_lds + ((b) * 2) * 16384 + vst1) = vr1; \
;     *(bf16x8*)(V_lds + ((b) * 2 + 1) * 16384 + vst1) = vr2; *(bf16x8*)(V_lds + ((b) * 2 + 1) * 16384 + vst0) = vr3; } while (0)
; #define QKH(P, b) do { P = f32x16{}; _Pragma("unroll") for (int d0 = 0; d0 < 8; ++d0) { const int cb = (d0 * 16 + hi * 8) * 2; \
;     const bf16x8 kf = *reinterpret_cast<const bf16x8*>(K_lds + (b) * 16384 + KSWZ(32 * kh + r32, cb)); P = __builtin_amdgcn_mfma_f32_32x32x16_bf16(kf, qr[d0], P, 0, 0, 0); } } while (0)
; __device__ __forceinline__ void attn_dv256_body(const bf16* __restrict__ Qb, const bf16* __restrict__ Kh, const bf16* __restrict__ Vh,
;                                                 float* __restrict__ Ob, int seq, float kmax, char* lds) {
;     ...
;   const int NT = seq / KVBLK;
;   f32x16 pc, pn; pn = f32x16{};
;   bf16x8 q0 = {}, q1 = {}, q2 = {}, q3 = {};
;   char* XC0 = XCH;
;   KLOAD(0); VLOAD(0); asm volatile("s_waitcnt vmcnt(0)" ::: "memory"); KWRITE(0); VWRITE(0);
;   KLOAD(KVBLK); VLOAD(KVBLK); asm volatile("s_waitcnt vmcnt(0)" ::: "memory"); KWRITE(1); VWRITE(1);
;   __syncthreads();
;   QKH(pc, 0);
;   KLOAD((2 < NT ? 2 : NT - 1) * KVBLK);
;   __syncthreads();
	ds_read_b128 v[8:11], v8
	v_cmp_lt_f32_e64 s[0:1], 0, v6
	v_lshlrev_b32_e32 v188, 2, v40
	ds_bpermute_b32 v40, v188, v54
	v_cndmask_b32_e64 v5, v7, v5, s[0:1]
	v_add_u32_e32 v7, v197, v199
	ds_read_b128 v[12:15], v7
	s_waitcnt lgkmcnt(2)
	v_mfma_f32_32x32x16_bf16 v[64:79], v[8:11], v[80:83], 0
	v_mul_f32_e32 v6, 0x37800000, v5
	v_cndmask_b32_e32 v5, v5, v6, vcc
	s_waitcnt lgkmcnt(1)
	v_add_f32_e32 v6, v54, v40
	v_mul_f32_e32 v7, 0x4f800000, v6
	v_cmp_gt_f32_e32 vcc, s22, v6
	v_bitop3_b32 v200, v164, v16, 64 bitop3:0x36
	v_lshlrev_b32_e32 v3, 1, v3
	v_cndmask_b32_e32 v17, v6, v7, vcc
	v_add_u32_e32 v6, v197, v200
	ds_read_b128 v[6:9], v6
	s_waitcnt lgkmcnt(1)
	v_mfma_f32_32x32x16_bf16 v[64:79], v[12:15], v[84:87], v[64:79]
	v_mov_b32_e32 v15, 0x260
	v_cmp_class_f32_e64 s[0:1], v4, v15
	v_sqrt_f32_e32 v18, v17
	v_and_b32_e32 v3, 32, v3
	v_cndmask_b32_e64 v14, v5, v4, s[0:1]
	s_movk_i32 s0, 0x60
	v_bitop3_b32 v201, v164, v16, s0 bitop3:0x36
	v_add_u32_e32 v5, v197, v201
	ds_read_b128 v[10:13], v5
	s_waitcnt lgkmcnt(1)
	v_mfma_f32_32x32x16_bf16 v[64:79], v[6:9], v[88:91], v[64:79]
	v_add_u32_e32 v4, -1, v18
	v_fma_f32 v5, -v4, v18, v17
	v_cmp_ge_f32_e64 s[0:1], 0, v5
	v_add_u32_e32 v9, 1, v18
	v_lshl_add_u64 v[166:167], s[38:39], 0, v[0:1]
	v_cndmask_b32_e64 v8, v18, v4, s[0:1]
	s_movk_i32 s0, 0x80
	v_bitop3_b32 v202, v164, v16, s0 bitop3:0x36
	v_add_u32_e32 v4, v197, v202
	ds_read_b128 v[4:7], v4
	s_waitcnt lgkmcnt(1)
	v_mfma_f32_32x32x16_bf16 v[64:79], v[10:13], v[92:95], v[64:79]
	v_fma_f32 v10, -v9, v18, v17
	v_cmp_lt_f32_e64 s[0:1], 0, v10
	v_lshl_add_u64 v[168:169], s[40:41], 0, v[0:1]
	v_mov_b32_e32 v18, v192
	v_cndmask_b32_e64 v12, v8, v9, s[0:1]
	s_movk_i32 s0, 0xa0
	v_bitop3_b32 v203, v164, v16, s0 bitop3:0x36
	v_add_u32_e32 v8, v197, v203
	ds_read_b128 v[8:11], v8
	s_waitcnt lgkmcnt(1)
	v_mfma_f32_32x32x16_bf16 v[64:79], v[4:7], v[96:99], v[64:79]
	v_mul_f32_e32 v13, 0x37800000, v12
	v_cndmask_b32_e32 v4, v12, v13, vcc
	v_cmp_class_f32_e32 vcc, v17, v15
	s_movk_i32 s0, 0xc0
	v_bitop3_b32 v204, v164, v16, s0 bitop3:0x36
	v_cndmask_b32_e32 v4, v4, v17, vcc
	v_mul_f32_e32 v12, v14, v4
	v_add_u32_e32 v4, v197, v204
	ds_read_b128 v[4:7], v4
	s_waitcnt lgkmcnt(1)
	v_mfma_f32_32x32x16_bf16 v[64:79], v[8:11], v[100:103], v[64:79]
	s_movk_i32 s0, 0xe0
	v_bitop3_b32 v206, v164, v16, s0 bitop3:0x36
	v_add_u32_e32 v8, v197, v206
	v_lshlrev_b32_e32 v14, 3, v191
	ds_read_b128 v[8:11], v8
	v_lshlrev_b32_e32 v13, 14, v187
	v_mul_f32_e32 v12, 0x3e0293ee, v12
	s_waitcnt lgkmcnt(1)
	v_mfma_f32_32x32x16_bf16 v[64:79], v[4:7], v[104:107], v[64:79]
	v_and_b32_e32 v4, 0xc0, v205
	v_and_or_b32 v4, v14, 24, v4
	v_and_b32_e32 v5, 0x100, v14
	v_or3_b32 v3, v4, v3, v5
	v_add3_u32 v207, v13, s13, v3
	v_add_u32_e32 v3, 0x80, v189
	v_mov_b64_e32 v[4:5], s[38:39]
	v_mad_i64_i32 v[6:7], s[22:23], v3, s93, v[4:5]
	v_add_u32_e32 v3, 0xa0, v189
	v_lshl_add_u64 v[6:7], v[6:7], 0, v[0:1]
	v_mad_i64_i32 v[4:5], s[22:23], v3, s93, v[4:5]
	v_lshl_add_u64 v[4:5], v[4:5], 0, v[0:1]
	s_waitcnt lgkmcnt(0)
	v_mfma_f32_32x32x16_bf16 v[64:79], v[8:11], v[108:111], v[64:79]
	v_mul_f32_e32 v208, 0xbf804189, v12
	s_add_i32 s0, s6, -1
	v_mov_b32_e32 v0, 0
	v_mov_b32_e32 v1, v192
	v_mov_b32_e32 v3, v192
	v_mov_b32_e32 v4, v192
	v_mov_b32_e32 v5, v192
	v_mov_b32_e32 v6, v192
	v_mov_b32_e32 v7, v192
	v_mov_b32_e32 v8, v192
	v_mov_b32_e32 v9, v192
	v_mov_b32_e32 v10, v192
	v_mov_b32_e32 v11, v192
	v_mov_b32_e32 v12, v192
	v_mov_b32_e32 v13, v192
	v_mov_b32_e32 v14, v192
	v_mov_b32_e32 v15, v192
	v_mov_b32_e32 v16, 0
	v_mov_b32_e32 v17, v192
	v_mov_b32_e32 v19, v192
	v_mov_b32_e32 v20, v192
	v_mov_b32_e32 v21, v192
	v_mov_b32_e32 v22, v192
	v_mov_b32_e32 v23, v192
	v_mov_b32_e32 v24, v192
	v_mov_b32_e32 v25, v192
	v_mov_b32_e32 v26, v192
	v_mov_b32_e32 v27, v192
	v_mov_b32_e32 v28, v192
	v_mov_b32_e32 v29, v192
	v_mov_b32_e32 v30, v192
	v_mov_b32_e32 v31, v192
	v_mov_b32_e32 v32, 0
	v_mov_b32_e32 v33, v192
	v_mov_b32_e32 v34, v192
	v_mov_b32_e32 v35, v192
	v_mov_b32_e32 v36, v192
	v_mov_b32_e32 v37, v192
	v_mov_b32_e32 v38, v192
	v_mov_b32_e32 v39, v192
	v_mov_b32_e32 v40, v192
	v_mov_b32_e32 v41, v192
	v_mov_b32_e32 v42, v192
	v_mov_b32_e32 v43, v192
	v_mov_b32_e32 v44, v192
	v_mov_b32_e32 v45, v192
	v_mov_b32_e32 v46, v192
	v_mov_b32_e32 v47, v192
	v_mov_b32_e32 v48, 0
	v_mov_b32_e32 v49, v192
	v_mov_b32_e32 v50, v192
	v_mov_b32_e32 v51, v192
	v_mov_b32_e32 v52, v192
	v_mov_b32_e32 v53, v192
	v_mov_b32_e32 v54, v192
	s_barrier
	v_bfe_u32 v142, v170, 2, 1
	v_xor_b32_e32 v189, v189, v142
	v_xor_b32_e32 v190, v190, v142
	v_lshlrev_b32_e32 v142, 6, v142
	v_xor_b32_e32 v193, v193, v142
	v_xor_b32_e32 v194, v194, v142
	s_min_u32 s100, s0, 1
	s_lshl_b32 s100, s100, 6
	v_add_u32_e32 v116, s100, v189
	v_add_u32_e32 v117, s100, v190
	v_mad_i64_i32 v[120:121], s[22:23], v116, s93, v[168:169]
	v_mad_i64_i32 v[124:125], s[22:23], v117, s93, v[168:169]
	global_load_dwordx4 v[112:115], v[124:125], off
	global_load_dwordx4 v[116:119], v[120:121], off
	s_nop 0
	global_load_dwordx4 v[120:123], v[120:121], off offset:256
	global_load_dwordx4 v[124:127], v[124:125], off offset:256
	v_and_b32_e32 v142, 63, v170
	v_lshrrev_b32_e32 v143, 4, v142
	v_and_b32_e32 v142, 15, v142
	v_xor_b32_e32 v140, v142, v143
	v_or_b32_e32 v141, 4, v143
	v_xor_b32_e32 v141, v142, v141
	v_lshlrev_b32_e32 v140, 4, v140
	v_lshlrev_b32_e32 v141, 4, v141
	v_lshrrev_b32_e32 v142, 6, v170
	v_lshl_add_u32 v142, v142, 3, v143
	v_mul_u32_u24_e32 v143, 0x4080, v142
	v_add_u32_e32 v140, v140, v143
	v_add_u32_e32 v143, 0xfe00, v143
	v_add_u32_e32 v141, v141, v143
	v_readfirstlane_b32 s101, v170
	s_nop 3
	s_lshr_b32 s101, s101, 6
	s_lshl_b32 s101, s101, 11
	s_add_i32 s101, s101, 0x10000
	s_min_u32 s100, s0, 2
	s_lshl_b32 s100, s100, 6
	s_mul_i32 s100, s100, 0x4080
	s_mov_b32 m0, s101
	v_add_u32_e32 v142, s100, v140
	v_add_u32_e32 v143, s100, v141
	global_load_lds_dwordx4 v142, s[38:39]
	global_load_lds_dwordx4 v143, s[38:39] offset:1024
; #define KWRITE(b) do { *(bf16x8*)(K_lds + (b) * 16384 + KSWZ(sr, sc * 2)) = kr0; *(bf16x8*)(K_lds + (b) * 16384 + KSWZ(32 + sr, sc * 2)) = kr1; } while (0)
; #define QKH(P, b) do { P = f32x16{}; _Pragma("unroll") for (int d0 = 0; d0 < 8; ++d0) { const int cb = (d0 * 16 + hi * 8) * 2; \
;     const bf16x8 kf = *reinterpret_cast<const bf16x8*>(K_lds + (b) * 16384 + KSWZ(32 * kh + r32, cb)); P = __builtin_amdgcn_mfma_f32_32x32x16_bf16(kf, qr[d0], P, 0, 0, 0); } } while (0)
; __device__ __forceinline__ void attn_dv256_body(const bf16* __restrict__ Qb, const bf16* __restrict__ Kh, const bf16* __restrict__ Vh,
;                                                 float* __restrict__ Ob, int seq, float kmax, char* lds) {
;     ...
;   for (int j = 0; j < NT; ++j) {
;     const int b = j & 1;
;     PvT T;
;     pv2_issue<2, 3>(T, vb0 + (b ^ 1) * 32768);
;     QKH(pn, b ^ 1);
;     float ps = 0.f;
; #pragma unroll
;     for (int r = 0; r < 16; ++r) { pc[r] = __builtin_amdgcn_exp2f(fmaf(pc[r], C, mC)); ps += pc[r]; }
;     l_reg += ps;
;     pv2_mma(o[2], o[3], T, q0, q1, q2, q3);
;     pv2_issue<0, 1>(T, vb0 + (b ^ 1) * 32768);
;     bf16x8 own0, own1; PK4(pc, 0, own0); PK4(pc, 8, own1);
;     *(bf16x8*)(XC0 + b * 16384 + ((wid * 2 + 0) * 64 + lane) * 16) = own0; *(bf16x8*)(XC0 + b * 16384 + ((wid * 2 + 1) * 64 + lane) * 16) = own1;
;     KWRITE(b);
;     pv2_mma(o[0], o[1], T, q0, q1, q2, q3);
.LBB0_910:
	s_and_b32 s1, s7, 1
	s_xor_b32 s22, s1, 1
	s_lshl_b32 s13, s22, 15
	v_add_u32_e32 v247, s13, v207
	ds_read_b64_tr_b16 v[152:153], v247 offset:0x400
	ds_read_b64_tr_b16 v[154:155], v247 offset:0xc00
	ds_read_b64_tr_b16 v[156:157], v247 offset:0x1400
	ds_read_b64_tr_b16 v[158:159], v247 offset:0x1c00
	ds_read_b64_tr_b16 v[160:161], v247 offset:0x2400
	ds_read_b64_tr_b16 v[162:163], v247 offset:0x2c00
	ds_read_b64_tr_b16 v[210:211], v247 offset:0x3400
	ds_read_b64_tr_b16 v[212:213], v247 offset:0x3c00
	ds_read_b64_tr_b16 v[214:215], v247 offset:0x600
	ds_read_b64_tr_b16 v[216:217], v247 offset:0xe00
	ds_read_b64_tr_b16 v[218:219], v247 offset:0x1600
	ds_read_b64_tr_b16 v[220:221], v247 offset:0x1e00
	ds_read_b64_tr_b16 v[222:223], v247 offset:0x2600
	ds_read_b64_tr_b16 v[224:225], v247 offset:0x2e00
	v_lshl_add_u32 v246, s22, 14, v197
	ds_read_b64_tr_b16 v[226:227], v247 offset:0x3600
	v_fmamk_f32 v174, v64, 0x3e0293ee, v208
	v_add_u32_e32 v64, v246, v198
	ds_read_b64_tr_b16 v[228:229], v247 offset:0x3e00
	v_fmamk_f32 v175, v65, 0x3e0293ee, v208
	v_fmamk_f32 v181, v66, 0x3e0293ee, v208
	v_fmamk_f32 v182, v67, 0x3e0293ee, v208
	ds_read_b128 v[64:67], v64
	v_fmamk_f32 v238, v68, 0x3e0293ee, v208
	v_add_u32_e32 v68, v246, v199
	ds_read_b128 v[230:233], v68
	v_fmamk_f32 v239, v69, 0x3e0293ee, v208
	v_fmamk_f32 v240, v70, 0x3e0293ee, v208
	v_fmamk_f32 v241, v71, 0x3e0293ee, v208
	v_fmamk_f32 v242, v72, 0x3e0293ee, v208
	v_fmamk_f32 v243, v73, 0x3e0293ee, v208
	v_fmamk_f32 v244, v74, 0x3e0293ee, v208
	v_fmamk_f32 v245, v75, 0x3e0293ee, v208
	v_fmamk_f32 v248, v76, 0x3e0293ee, v208
	v_fmamk_f32 v249, v77, 0x3e0293ee, v208
	v_fmamk_f32 v250, v78, 0x3e0293ee, v208
	v_fmamk_f32 v173, v79, 0x3e0293ee, v208
	s_waitcnt lgkmcnt(1)
	v_mfma_f32_32x32x16_bf16 v[64:79], v[64:67], v[80:83], 0
	v_add_u32_e32 v234, v246, v200
	v_exp_f32_e32 v174, v174
	v_exp_f32_e32 v175, v175
	v_exp_f32_e32 v181, v181
	v_exp_f32_e32 v182, v182
	v_exp_f32_e32 v238, v238
	v_exp_f32_e32 v239, v239
	s_waitcnt lgkmcnt(0)
	v_mfma_f32_32x32x16_bf16 v[64:79], v[230:233], v[84:87], v[64:79]
	ds_read_b128 v[230:233], v234
	v_add_u32_e32 v234, v246, v201
	ds_read_b128 v[234:237], v234
	v_exp_f32_e32 v240, v240
	v_exp_f32_e32 v241, v241
	v_exp_f32_e32 v242, v242
	v_exp_f32_e32 v243, v243
	s_waitcnt lgkmcnt(1)
	v_mfma_f32_32x32x16_bf16 v[64:79], v[230:233], v[88:91], v[64:79]
	v_add_u32_e32 v230, v246, v202
	ds_read_b128 v[230:233], v230
	v_exp_f32_e32 v244, v244
	v_exp_f32_e32 v245, v245
	v_exp_f32_e32 v248, v248
	v_exp_f32_e32 v249, v249
	v_exp_f32_e32 v250, v250
	s_waitcnt lgkmcnt(1)
	v_mfma_f32_32x32x16_bf16 v[64:79], v[234:237], v[92:95], v[64:79]
	v_add_u32_e32 v234, v246, v203
	ds_read_b128 v[234:237], v234
	v_exp_f32_e32 v173, v173
	s_waitcnt lgkmcnt(1)
	v_mfma_f32_32x32x16_bf16 v[64:79], v[230:233], v[96:99], v[64:79]
	v_add_u32_e32 v230, v246, v204
	ds_read_b128 v[230:233], v230
	s_waitcnt lgkmcnt(1)
	v_mfma_f32_32x32x16_bf16 v[64:79], v[234:237], v[100:103], v[64:79]
	v_add_f32_e32 v235, 0, v174
	v_add_f32_e32 v235, v175, v235
	v_add_u32_e32 v234, v246, v206
	v_add_f32_e32 v235, v181, v235
	v_add_f32_e32 v246, v182, v235
	ds_read_b128 v[234:237], v234
	s_waitcnt lgkmcnt(0)
	s_waitcnt lgkmcnt(1)
	v_mfma_f32_32x32x16_bf16 v[64:79], v[230:233], v[104:107], v[64:79]
	v_add_f32_e32 v230, v238, v246
	v_add_f32_e32 v230, v239, v230
	v_add_f32_e32 v230, v240, v230
	v_add_f32_e32 v230, v241, v230
	v_add_f32_e32 v230, v242, v230
	v_add_f32_e32 v230, v243, v230
	v_add_f32_e32 v230, v244, v230
	s_waitcnt lgkmcnt(0)
	v_mfma_f32_32x32x16_bf16 v[64:79], v[234:237], v[108:111], v[64:79]
	v_add_f32_e32 v230, v245, v230
	v_add_f32_e32 v230, v248, v230
	v_add_f32_e32 v230, v249, v230
	v_add_f32_e32 v230, v250, v230
	v_add_f32_e32 v230, v173, v230
	v_add_f32_e32 v192, v192, v230
	v_cvt_pk_bf16_f32 v241, v240, v241
	v_cvt_pk_bf16_f32 v240, v238, v239
	v_cvt_pk_bf16_f32 v239, v181, v182
	v_cvt_pk_bf16_f32 v238, v174, v175
	v_cvt_pk_bf16_f32 v242, v242, v243
	v_cvt_pk_bf16_f32 v243, v244, v245
	v_cvt_pk_bf16_f32 v244, v248, v249
	v_cvt_pk_bf16_f32 v245, v250, v173
	s_lshl_b32 s1, s1, 14
	s_add_i32 s1, s1, 0
	s_add_i32 s35, s1, 0x18000
	s_add_i32 s1, s1, 0x10000
	v_permlane32_swap_b32_e32 v238, v240
	v_permlane32_swap_b32_e32 v239, v241
	v_add3_u32 v173, s35, v209, v205
	v_permlane32_swap_b32_e32 v242, v244
	v_permlane32_swap_b32_e32 v243, v245
	ds_write_b128 v173, v[238:241]
	ds_write_b128 v173, v[242:245] offset:1024
	v_mfma_f32_32x32x16_bf16 v[32:47], v[144:147], v[152:155], v[32:47]
	v_mfma_f32_32x32x16_bf16 v[48:63], v[144:147], v[214:217], v[48:63]
	v_mfma_f32_32x32x16_bf16 v[32:47], v[148:151], v[156:159], v[32:47]
	v_mfma_f32_32x32x16_bf16 v[48:63], v[148:151], v[218:221], v[48:63]
	v_mfma_f32_32x32x16_bf16 v[32:47], v[132:135], v[160:163], v[32:47]
	v_mfma_f32_32x32x16_bf16 v[48:63], v[132:135], v[222:225], v[48:63]
	v_mfma_f32_32x32x16_bf16 v[32:47], v[128:131], v[210:213], v[32:47]
	ds_read_b64_tr_b16 v[210:211], v247 offset:0
	ds_read_b64_tr_b16 v[212:213], v247 offset:0x800
	ds_read_b64_tr_b16 v[214:215], v247 offset:0x1000
	ds_read_b64_tr_b16 v[216:217], v247 offset:0x1800
	ds_read_b64_tr_b16 v[218:219], v247 offset:0x2000
	ds_read_b64_tr_b16 v[220:221], v247 offset:0x2800
	ds_read_b64_tr_b16 v[222:223], v247 offset:0x3000
	ds_read_b64_tr_b16 v[224:225], v247 offset:0x3800
	v_mfma_f32_32x32x16_bf16 v[48:63], v[128:131], v[226:229], v[48:63]
	ds_read_b64_tr_b16 v[226:227], v247 offset:0x200
	ds_read_b64_tr_b16 v[228:229], v247 offset:0xa00
	ds_read_b64_tr_b16 v[230:231], v247 offset:0x1200
	ds_read_b64_tr_b16 v[232:233], v247 offset:0x1a00
	ds_read_b64_tr_b16 v[234:235], v247 offset:0x2200
	ds_read_b64_tr_b16 v[236:237], v247 offset:0x2a00
	ds_read_b64_tr_b16 v[160:161], v247 offset:0x3200
	ds_read_b64_tr_b16 v[162:163], v247 offset:0x3a00
	s_waitcnt lgkmcnt(0)
	s_add_i32 s1, s13, 0
	s_add_i32 s13, s7, 3
	s_add_i32 s22, s7, 2
	v_add_u32_e32 v136, s1, v193
	v_add_u32_e32 v137, s1, v194
	s_min_u32 s1, s13, s0
	s_min_u32 s13, s22, s0
	s_lshl_b32 s1, s1, 6
	s_lshl_b32 s13, s13, 6
	s_waitcnt vmcnt(0)
	s_waitcnt lgkmcnt(0)
	s_barrier
; #define KLOAD(k0) do { kr0 = St::ld8(&Kh[(long)((k0) + sr) * LDK + sc]); kr1 = St::ld8(&Kh[(long)((k0) + 32 + sr) * LDK + sc]); } while (0)
; #define VLOAD(k0) do { vr0 = St::ld8(&Vh[(long)((k0) + sr) * LDK + sc]); vr1 = St::ld8(&Vh[(long)((k0) + 32 + sr) * LDK + sc]); \
;     vr2 = St::ld8(&Vh[(long)((k0) + sr) * LDK + 128 + sc]); vr3 = St::ld8(&Vh[(long)((k0) + 32 + sr) * LDK + 128 + sc]); } while (0)
; #define VWRITE(b) do { *(bf16x8*)(V_lds + ((b) * 2) * 16384 + vst0) = vr0; *(bf16x8*)(V_lds + ((b) * 2) * 16384 + vst1) = vr1; \
;     *(bf16x8*)(V_lds + ((b) * 2 + 1) * 16384 + vst1) = vr2; *(bf16x8*)(V_lds + ((b) * 2 + 1) * 16384 + vst0) = vr3; } while (0)
; __device__ __forceinline__ void attn_dv256_body(const bf16* __restrict__ Qb, const bf16* __restrict__ Kh, const bf16* __restrict__ Vh,
;                                                 float* __restrict__ Ob, int seq, float kmax, char* lds) {
;     ...
;     __syncthreads();
;     VWRITE(b ^ 1);
;     { const int kt = (j + 3 < NT) ? j + 3 : NT - 1, vt = (j + 2 < NT) ? j + 2 : NT - 1; KLOAD(kt * KVBLK); VLOAD(vt * KVBLK); }
;     q0 = own0; q1 = own1;
;     q2 = *(const bf16x8*)(XC0 + b * 16384 + (((wid ^ 4) * 2 + 0) * 64 + lane) * 16); q3 = *(const bf16x8*)(XC0 + b * 16384 + (((wid ^ 4) * 2 + 1) * 64 + lane) * 16);
;     pc = pn;
;   }
;   { PvT T; const int vl = vb0 + ((NT - 1) & 1) * 32768;
;     pv2_issue<2, 3>(T, vl); pv2_mma(o[2], o[3], T, q0, q1, q2, q3); pv2_issue<0, 1>(T, vl); pv2_mma(o[0], o[1], T, q0, q1, q2, q3); }
	s_xor_b32 s101, s101, 0x4000
	s_mul_i32 s100, s1, 0x4080
	s_mov_b32 m0, s101
	v_add_u32_e32 v142, s100, v140
	v_add_u32_e32 v143, s100, v141
	global_load_lds_dwordx4 v142, s[38:39]
	global_load_lds_dwordx4 v143, s[38:39] offset:1024
	ds_write_b128 v136, v[116:119]
	ds_write_b128 v137, v[112:115]
	v_add_u32_e32 v116, s13, v189
	ds_write_b128 v137, v[120:123] offset:16384
	ds_write_b128 v136, v[124:127] offset:16384
	v_add_u32_e32 v117, s13, v190
	v_mad_i64_i32 v[120:121], s[22:23], v116, s93, v[168:169]
	v_mad_i64_i32 v[124:125], s[22:23], v117, s93, v[168:169]
	s_nop 0
	global_load_dwordx4 v[112:115], v[124:125], off
	global_load_dwordx4 v[116:119], v[120:121], off
	s_nop 0
	global_load_dwordx4 v[120:123], v[120:121], off offset:256
	v_mfma_f32_32x32x16_bf16 v[0:15], v[144:147], v[210:213], v[0:15]
	global_load_dwordx4 v[124:127], v[124:125], off offset:256
	s_add_i32 s7, s7, 1
	s_cmp_eq_u32 s6, s7
	v_mfma_f32_32x32x16_bf16 v[16:31], v[144:147], v[226:229], v[16:31]
	v_mov_b32_e32 v144, v238
	v_mov_b32_e32 v145, v239
	v_mov_b32_e32 v146, v240
	v_mov_b32_e32 v147, v241
	v_mfma_f32_32x32x16_bf16 v[0:15], v[148:151], v[214:217], v[0:15]
	v_mfma_f32_32x32x16_bf16 v[16:31], v[148:151], v[230:233], v[16:31]
	v_mov_b32_e32 v149, v243
	v_mov_b32_e32 v150, v244
	v_mov_b32_e32 v151, v245
	v_mfma_f32_32x32x16_bf16 v[0:15], v[132:135], v[218:221], v[0:15]
	v_mfma_f32_32x32x16_bf16 v[16:31], v[132:135], v[234:237], v[16:31]
	v_bitop3_b32 v132, v209, s95, v205 bitop3:0x36
	v_add_u32_e32 v148, s35, v132
	v_mfma_f32_32x32x16_bf16 v[0:15], v[128:131], v[222:225], v[0:15]
	v_mfma_f32_32x32x16_bf16 v[16:31], v[128:131], v[160:163], v[16:31]
	ds_read_b128 v[132:135], v148
	ds_read_b128 v[128:131], v148 offset:1024
	v_mov_b32_e32 v148, v242
	s_cbranch_scc0 .LBB0_910
	s_waitcnt vmcnt(0)
	v_mov_b32_e32 v152, v238
	v_mov_b32_e32 v153, v239
	v_mov_b32_e32 v154, v240
	v_mov_b32_e32 v155, v241
	v_mov_b32_e32 v156, v242
	v_mov_b32_e32 v157, v243
	v_mov_b32_e32 v158, v244
	v_mov_b32_e32 v159, v245
	v_add_u32_e32 v96, 0x8000, v207
	ds_read_b64_tr_b16 v[64:65], v96 offset:0x400
	ds_read_b64_tr_b16 v[66:67], v96 offset:0xc00
	ds_read_b64_tr_b16 v[68:69], v96 offset:0x1400
	ds_read_b64_tr_b16 v[70:71], v96 offset:0x1c00
	ds_read_b64_tr_b16 v[72:73], v96 offset:0x2400
	ds_read_b64_tr_b16 v[74:75], v96 offset:0x2c00
	ds_read_b64_tr_b16 v[76:77], v96 offset:0x3400
	ds_read_b64_tr_b16 v[78:79], v96 offset:0x3c00
	ds_read_b64_tr_b16 v[80:81], v96 offset:0x600
	ds_read_b64_tr_b16 v[82:83], v96 offset:0xe00
	ds_read_b64_tr_b16 v[84:85], v96 offset:0x1600
	ds_read_b64_tr_b16 v[86:87], v96 offset:0x1e00
	ds_read_b64_tr_b16 v[88:89], v96 offset:0x2600
	ds_read_b64_tr_b16 v[90:91], v96 offset:0x2e00
	ds_read_b64_tr_b16 v[92:93], v96 offset:0x3600
	ds_read_b64_tr_b16 v[94:95], v96 offset:0x3e00
	s_waitcnt lgkmcnt(0)
	s_nop 0
	v_mfma_f32_32x32x16_bf16 v[32:47], v[152:155], v[64:67], v[32:47]
	ds_read_b64_tr_b16 v[64:65], v96 offset:0
	ds_read_b64_tr_b16 v[66:67], v96 offset:0x800
	v_mfma_f32_32x32x16_bf16 v[48:63], v[152:155], v[80:83], v[48:63]
	v_mfma_f32_32x32x16_bf16 v[32:47], v[156:159], v[68:71], v[32:47]
	ds_read_b64_tr_b16 v[68:69], v96 offset:0x1000
	ds_read_b64_tr_b16 v[70:71], v96 offset:0x1800
	v_mfma_f32_32x32x16_bf16 v[48:63], v[156:159], v[84:87], v[48:63]
	s_waitcnt lgkmcnt(1)
	v_mfma_f32_32x32x16_bf16 v[32:47], v[132:135], v[72:75], v[32:47]
	ds_read_b64_tr_b16 v[72:73], v96 offset:0x2000
	ds_read_b64_tr_b16 v[74:75], v96 offset:0x2800
	v_mfma_f32_32x32x16_bf16 v[48:63], v[132:135], v[88:91], v[48:63]
	s_waitcnt lgkmcnt(0)
	v_mfma_f32_32x32x16_bf16 v[32:47], v[128:131], v[76:79], v[32:47]
	ds_read_b64_tr_b16 v[76:77], v96 offset:0x3000
	ds_read_b64_tr_b16 v[78:79], v96 offset:0x3800
	ds_read_b64_tr_b16 v[80:81], v96 offset:0x200
	ds_read_b64_tr_b16 v[82:83], v96 offset:0xa00
	ds_read_b64_tr_b16 v[84:85], v96 offset:0x1200
	ds_read_b64_tr_b16 v[86:87], v96 offset:0x1a00
	ds_read_b64_tr_b16 v[88:89], v96 offset:0x2200
	v_mfma_f32_32x32x16_bf16 v[48:63], v[128:131], v[92:95], v[48:63]
	ds_read_b64_tr_b16 v[90:91], v96 offset:0x2a00
	ds_read_b64_tr_b16 v[92:93], v96 offset:0x3200
	ds_read_b64_tr_b16 v[94:95], v96 offset:0x3a00
	s_waitcnt lgkmcnt(0)
	v_mfma_f32_32x32x16_bf16 v[0:15], v[152:155], v[64:67], v[0:15]
	ds_bpermute_b32 v66, v188, v192
	v_cmp_gt_u32_e32 vcc, 32, v191
	v_lshlrev_b32_e32 v65, 2, v185
	v_lshlrev_b32_e32 v64, 2, v186
	v_mfma_f32_32x32x16_bf16 v[16:31], v[152:155], v[80:83], v[16:31]
	v_mfma_f32_32x32x16_bf16 v[0:15], v[156:159], v[68:71], v[0:15]
	v_mfma_f32_32x32x16_bf16 v[16:31], v[156:159], v[84:87], v[16:31]
	v_mfma_f32_32x32x16_bf16 v[0:15], v[132:135], v[72:75], v[0:15]
	v_mfma_f32_32x32x16_bf16 v[16:31], v[132:135], v[88:91], v[16:31]
	v_mfma_f32_32x32x16_bf16 v[0:15], v[128:131], v[76:79], v[0:15]
	v_mfma_f32_32x32x16_bf16 v[16:31], v[128:131], v[92:95], v[16:31]
	s_and_saveexec_b64 s[0:1], vcc
	s_cbranch_execz .LBB0_913
	s_add_i32 s6, 0, 0x20000
	v_lshl_add_u32 v67, v187, 9, s6
	v_add3_u32 v67, v67, v65, v64
	s_waitcnt lgkmcnt(0)
	v_add_f32_e32 v66, v192, v66
	ds_write_b32 v67, v66

; __device__ __forceinline__ int tidx() { int t = threadIdx.x; asm volatile("" : "+v"(t)); return t; }
; #define LAS __attribute__((address_space(3)))
; __global__ void __launch_bounds__(512, 2) mega(Params p) {
;     extern __shared__ __attribute__((aligned(16))) unsigned char lds[];
;     cg::grid_group grid = cg::this_grid();
;     LAS unsigned char* L = (LAS unsigned char*)lds;
;     int tid = tidx(), lane = tid & 63, wave = tid >> 6; const int bid = blockIdx.x, G = gridDim.x;
	.amdhsa_kernel _Z4mega6Params
		.amdhsa_group_segment_fixed_size 0
		.amdhsa_private_segment_fixed_size 0
		.amdhsa_kernarg_size 416
		.amdhsa_user_sgpr_count 2
		.amdhsa_user_sgpr_dispatch_ptr 0
		.amdhsa_user_sgpr_queue_ptr 0
		.amdhsa_user_sgpr_kernarg_segment_ptr 1
		.amdhsa_user_sgpr_dispatch_id 0
		.amdhsa_user_sgpr_kernarg_preload_length 0
		.amdhsa_user_sgpr_kernarg_preload_offset 0
		.amdhsa_user_sgpr_private_segment_size 0
		.amdhsa_uses_dynamic_stack 0
		.amdhsa_enable_private_segment 0
		.amdhsa_system_sgpr_workgroup_id_x 1
		.amdhsa_system_sgpr_workgroup_id_y 0
		.amdhsa_system_sgpr_workgroup_id_z 0
		.amdhsa_system_sgpr_workgroup_info 0
		.amdhsa_system_vgpr_workitem_id 2
		.amdhsa_next_free_vgpr 256
		.amdhsa_next_free_sgpr 102
		.amdhsa_accum_offset 256
		.amdhsa_reserve_vcc 1
		.amdhsa_float_round_mode_32 0
		.amdhsa_float_round_mode_16_64 0
		.amdhsa_float_denorm_mode_32 3
		.amdhsa_float_denorm_mode_16_64 3
		.amdhsa_dx10_clamp 1
		.amdhsa_ieee_mode 1
		.amdhsa_fp16_overflow 0
		.amdhsa_tg_split 0
		.amdhsa_exception_fp_ieee_invalid_op 0
		.amdhsa_exception_fp_denorm_src 0
		.amdhsa_exception_fp_ieee_div_zero 0
		.amdhsa_exception_fp_ieee_overflow 0
		.amdhsa_exception_fp_ieee_underflow 0
		.amdhsa_exception_fp_ieee_inexact 0
		.amdhsa_exception_int_div_zero 0
	.end_amdhsa_kernel

; __global__ void __launch_bounds__(512, 2) mega(Params p) {
;     extern __shared__ __attribute__((aligned(16))) unsigned char lds[];
amdhsa.kernels:
  - .agpr_count:     0
    .args:
      - .offset:         0
        .size:           160
        .value_kind:     by_value
      - .offset:         160
        .size:           4
        .value_kind:     hidden_block_count_x
      - .offset:         164
        .size:           4
        .value_kind:     hidden_block_count_y
      - .offset:         168
        .size:           4
        .value_kind:     hidden_block_count_z
      - .offset:         172
        .size:           2
        .value_kind:     hidden_group_size_x
      - .offset:         174
        .size:           2
        .value_kind:     hidden_group_size_y
      - .offset:         176
        .size:           2
        .value_kind:     hidden_group_size_z
      - .offset:         178
        .size:           2
        .value_kind:     hidden_remainder_x
      - .offset:         180
        .size:           2
        .value_kind:     hidden_remainder_y
      - .offset:         182
        .size:           2
        .value_kind:     hidden_remainder_z
      - .offset:         200
        .size:           8
        .value_kind:     hidden_global_offset_x
      - .offset:         208
        .size:           8
        .value_kind:     hidden_global_offset_y
      - .offset:         216
        .size:           8
        .value_kind:     hidden_global_offset_z
      - .offset:         224
        .size:           2
        .value_kind:     hidden_grid_dims
      - .offset:         248
        .size:           8
        .value_kind:     hidden_multigrid_sync_arg
      - .offset:         280
        .size:           4
        .value_kind:     hidden_dynamic_lds_size
    .group_segment_fixed_size: 0
    .kernarg_segment_align: 8
    .kernarg_segment_size: 416
    .language:       OpenCL C
    .language_version:
      - 2
      - 0
    .max_flat_workgroup_size: 512
    .name:           _Z4mega6Params
    .private_segment_fixed_size: 0
    .sgpr_count:     108
    .sgpr_spill_count: 265
    .symbol:         _Z4mega6Params.kd
    .uniform_work_group_size: 1
    .uses_dynamic_stack: false
    .vgpr_count:     256
    .vgpr_spill_count: 0
    .wavefront_size: 64
